# v19 plus: LDS-DMA addressing in the int8 GEMM1 K-loop via SGPR base + 32-bit VGPR offset (no 64-bit VALU address adds in the load segments)
# speedup vs baseline: 1.0140x; 1.0067x over previous
.LBB0_300:
	s_add_u32 s100, s0, 0xfff80000
	s_addc_u32 s101, s1, -1
	s_add_u32 s28, s0, 0xfff80080
	s_addc_u32 s29, s1, -1
	s_add_i32 s42, 0, 0x10000
	s_cmp_eq_u32 s41, 28
	s_cselect_b32 s31, s18, s29
	s_cselect_b32 s30, s19, s28
	v_add_u32_e32 v0, s42, v199
	s_cselect_b32 s29, s27, s40
	s_cselect_b32 s28, s34, s35
	s_add_i32 s49, 0, 0x14000
	ds_read_b128 v[2:5], v0
	ds_read_b128 v[6:9], v0 offset:1024
	ds_read_b128 v[10:13], v0 offset:2048
	ds_read_b128 v[14:17], v0 offset:3072
	v_add_u32_e32 v0, s49, v199
	ds_read_b128 v[146:149], v0
	ds_read_b128 v[150:153], v0 offset:1024
	ds_read_b128 v[154:157], v0 offset:2048
	ds_read_b128 v[158:161], v0 offset:3072
	s_mov_b32 m0, s15
	ds_read_b128 v[174:177], v250
	ds_read_b128 v[178:181], v250 offset:1024
	ds_read_b128 v[182:185], v250 offset:2048
	ds_read_b128 v[186:189], v250 offset:3072
	ds_read_b128 v[190:193], v250 offset:4096
	ds_read_b128 v[200:203], v250 offset:5120
	ds_read_b128 v[204:207], v250 offset:6144
	ds_read_b128 v[208:211], v250 offset:7168
	global_load_lds_dwordx4 v162, s[100:101]
	s_mov_b32 m0, s88
	s_nop 0
	global_load_lds_dwordx4 v166, s[100:101]
	s_add_i32 m0, s21, 0xc000
	s_nop 0
	global_load_lds_dwordx4 v170, s[0:1]
	s_add_i32 m0, s21, 0xe000
	s_nop 0
	global_load_lds_dwordx4 v172, s[0:1]
	s_waitcnt vmcnt(8)
	s_waitcnt lgkmcnt(0)
	s_barrier
	s_waitcnt lgkmcnt(0)
	v_mfma_i32_16x16x64_i8 v[142:145], v[2:5], v[174:177], v[142:145]
	v_mfma_i32_16x16x64_i8 v[142:145], v[6:9], v[178:181], v[142:145]
	v_mfma_i32_16x16x64_i8 v[134:137], v[2:5], v[182:185], v[134:137]
	v_mfma_i32_16x16x64_i8 v[134:137], v[6:9], v[186:189], v[134:137]
	v_mfma_i32_16x16x64_i8 v[122:125], v[2:5], v[190:193], v[122:125]
	v_mfma_i32_16x16x64_i8 v[122:125], v[6:9], v[200:203], v[122:125]
	v_mfma_i32_16x16x64_i8 v[106:109], v[2:5], v[204:207], v[106:109]
	v_mfma_i32_16x16x64_i8 v[106:109], v[6:9], v[208:211], v[106:109]
	v_mfma_i32_16x16x64_i8 v[138:141], v[10:13], v[174:177], v[138:141]
	v_mfma_i32_16x16x64_i8 v[138:141], v[14:17], v[178:181], v[138:141]
	v_mfma_i32_16x16x64_i8 v[130:133], v[10:13], v[182:185], v[130:133]
	v_mfma_i32_16x16x64_i8 v[130:133], v[14:17], v[186:189], v[130:133]
	v_mfma_i32_16x16x64_i8 v[114:117], v[10:13], v[190:193], v[114:117]
	v_mfma_i32_16x16x64_i8 v[114:117], v[14:17], v[200:203], v[114:117]
	v_mfma_i32_16x16x64_i8 v[98:101], v[10:13], v[204:207], v[98:101]
	v_mfma_i32_16x16x64_i8 v[98:101], v[14:17], v[208:211], v[98:101]
	v_mfma_i32_16x16x64_i8 v[126:129], v[146:149], v[174:177], v[126:129]
	v_mfma_i32_16x16x64_i8 v[126:129], v[150:153], v[178:181], v[126:129]
	v_mfma_i32_16x16x64_i8 v[110:113], v[146:149], v[182:185], v[110:113]
	v_mfma_i32_16x16x64_i8 v[110:113], v[150:153], v[186:189], v[110:113]
	v_mfma_i32_16x16x64_i8 v[94:97], v[146:149], v[190:193], v[94:97]
	v_mfma_i32_16x16x64_i8 v[94:97], v[150:153], v[200:203], v[94:97]
	v_mfma_i32_16x16x64_i8 v[86:89], v[146:149], v[204:207], v[86:89]
	v_mfma_i32_16x16x64_i8 v[86:89], v[150:153], v[208:211], v[86:89]
	v_mfma_i32_16x16x64_i8 v[118:121], v[154:157], v[174:177], v[118:121]
	v_mfma_i32_16x16x64_i8 v[118:121], v[158:161], v[178:181], v[118:121]
	v_mfma_i32_16x16x64_i8 v[102:105], v[154:157], v[182:185], v[102:105]
	v_mfma_i32_16x16x64_i8 v[102:105], v[158:161], v[186:189], v[102:105]
	v_mfma_i32_16x16x64_i8 v[90:93], v[154:157], v[190:193], v[90:93]
	v_mfma_i32_16x16x64_i8 v[90:93], v[158:161], v[200:203], v[90:93]
	v_mfma_i32_16x16x64_i8 v[82:85], v[154:157], v[204:207], v[82:85]
	v_mfma_i32_16x16x64_i8 v[82:85], v[158:161], v[208:211], v[82:85]
	s_barrier
	s_add_i32 s42, s42, s81
	s_mov_b32 m0, s42
	ds_read_b128 v[174:177], v250 offset:16384
	ds_read_b128 v[178:181], v250 offset:17408
	ds_read_b128 v[182:185], v250 offset:18432
	ds_read_b128 v[186:189], v250 offset:19456
	ds_read_b128 v[190:193], v250 offset:20480
	ds_read_b128 v[200:203], v250 offset:21504
	ds_read_b128 v[204:207], v250 offset:22528
	ds_read_b128 v[208:211], v250 offset:23552
	global_load_lds_dwordx4 v164, s[28:29]
	s_add_i32 m0, s42, 0x2000
	s_add_u32 s42, s28, 0x80000
	s_addc_u32 s43, s29, 0
	s_add_i32 s49, s49, s81
	global_load_lds_dwordx4 v168, s[28:29]
	s_mov_b32 m0, s49
	s_nop 0
	global_load_lds_dwordx4 v164, s[42:43]
	s_add_i32 m0, s49, 0x2000
	s_nop 0
	global_load_lds_dwordx4 v168, s[42:43]
	s_waitcnt vmcnt(6)
	s_waitcnt lgkmcnt(0)
	s_barrier
	s_waitcnt lgkmcnt(0)
	v_mfma_i32_16x16x64_i8 v[78:81], v[2:5], v[174:177], v[78:81]
	v_mfma_i32_16x16x64_i8 v[78:81], v[6:9], v[178:181], v[78:81]
	v_mfma_i32_16x16x64_i8 v[74:77], v[10:13], v[174:177], v[74:77]
	v_mfma_i32_16x16x64_i8 v[74:77], v[14:17], v[178:181], v[74:77]
	v_mfma_i32_16x16x64_i8 v[70:73], v[2:5], v[182:185], v[70:73]
	v_mfma_i32_16x16x64_i8 v[70:73], v[6:9], v[186:189], v[70:73]
	v_mfma_i32_16x16x64_i8 v[66:69], v[10:13], v[182:185], v[66:69]
	v_mfma_i32_16x16x64_i8 v[66:69], v[14:17], v[186:189], v[66:69]
	v_mfma_i32_16x16x64_i8 v[54:57], v[2:5], v[190:193], v[54:57]
	v_mfma_i32_16x16x64_i8 v[54:57], v[6:9], v[200:203], v[54:57]
	v_mfma_i32_16x16x64_i8 v[50:53], v[10:13], v[190:193], v[50:53]
	v_mfma_i32_16x16x64_i8 v[50:53], v[14:17], v[200:203], v[50:53]
	v_mfma_i32_16x16x64_i8 v[2:5], v[2:5], v[204:207], v[38:41]
	v_mfma_i32_16x16x64_i8 v[2:5], v[6:9], v[208:211], v[2:5]
	v_mfma_i32_16x16x64_i8 v[6:9], v[10:13], v[204:207], v[34:37]
	v_mfma_i32_16x16x64_i8 v[6:9], v[14:17], v[208:211], v[6:9]
	v_mfma_i32_16x16x64_i8 v[34:37], v[146:149], v[182:185], v[46:49]
	v_mfma_i32_16x16x64_i8 v[46:49], v[150:153], v[186:189], v[34:37]
	v_mfma_i32_16x16x64_i8 v[34:37], v[154:157], v[182:185], v[42:45]
	v_mfma_i32_16x16x64_i8 v[42:45], v[158:161], v[186:189], v[34:37]
	v_mfma_i32_16x16x64_i8 v[30:33], v[146:149], v[190:193], v[30:33]
	v_mfma_i32_16x16x64_i8 v[30:33], v[150:153], v[200:203], v[30:33]
	v_mfma_i32_16x16x64_i8 v[26:29], v[154:157], v[190:193], v[26:29]
	v_mfma_i32_16x16x64_i8 v[26:29], v[158:161], v[200:203], v[26:29]
	v_mfma_i32_16x16x64_i8 v[22:25], v[146:149], v[204:207], v[22:25]
	v_mfma_i32_16x16x64_i8 v[22:25], v[150:153], v[208:211], v[22:25]
	v_mfma_i32_16x16x64_i8 v[18:21], v[154:157], v[204:207], v[18:21]
	v_mfma_i32_16x16x64_i8 v[18:21], v[158:161], v[208:211], v[18:21]
	v_mfma_i32_16x16x64_i8 v[10:13], v[146:149], v[174:177], v[62:65]
	v_mfma_i32_16x16x64_i8 v[10:13], v[150:153], v[178:181], v[10:13]
	v_mfma_i32_16x16x64_i8 v[14:17], v[154:157], v[174:177], v[58:61]
	v_mfma_i32_16x16x64_i8 v[14:17], v[158:161], v[178:181], v[14:17]
	s_barrier
	s_add_i32 s42, 0, 0x18000
	v_add_u32_e32 v0, s42, v199
	s_add_i32 s43, 0, 0x1c000
	ds_read_b128 v[34:37], v0
	ds_read_b128 v[38:41], v0 offset:1024
	ds_read_b128 v[58:61], v0 offset:2048
	ds_read_b128 v[62:65], v0 offset:3072
	v_add_u32_e32 v0, s43, v199
	ds_read_b128 v[146:149], v0
	ds_read_b128 v[150:153], v0 offset:1024
	ds_read_b128 v[154:157], v0 offset:2048
	ds_read_b128 v[158:161], v0 offset:3072
	s_mov_b32 m0, s21
	ds_read_b128 v[174:177], v250 offset:32768
	ds_read_b128 v[178:181], v250 offset:33792
	ds_read_b128 v[182:185], v250 offset:34816
	ds_read_b128 v[186:189], v250 offset:35840
	ds_read_b128 v[190:193], v250 offset:36864
	ds_read_b128 v[200:203], v250 offset:37888
	ds_read_b128 v[204:207], v250 offset:38912
	ds_read_b128 v[208:211], v250 offset:39936
	global_load_lds_dwordx4 v162, s[30:31]
	s_mov_b32 m0, s57
	s_nop 0
	global_load_lds_dwordx4 v166, s[30:31]
	s_add_u32 s30, s30, 0x80000
	s_addc_u32 s31, s31, 0
	s_mov_b32 m0, s73
	s_nop 0
	global_load_lds_dwordx4 v162, s[30:31]
	s_mov_b32 m0, s76
	s_nop 0
	global_load_lds_dwordx4 v166, s[30:31]
	s_waitcnt vmcnt(8)
	s_waitcnt lgkmcnt(0)
	s_barrier
	s_waitcnt lgkmcnt(0)
	v_mfma_i32_16x16x64_i8 v[142:145], v[34:37], v[174:177], v[142:145]
	v_mfma_i32_16x16x64_i8 v[142:145], v[38:41], v[178:181], v[142:145]
	v_mfma_i32_16x16x64_i8 v[134:137], v[34:37], v[182:185], v[134:137]
	v_mfma_i32_16x16x64_i8 v[134:137], v[38:41], v[186:189], v[134:137]
	v_mfma_i32_16x16x64_i8 v[122:125], v[34:37], v[190:193], v[122:125]
	v_mfma_i32_16x16x64_i8 v[122:125], v[38:41], v[200:203], v[122:125]
	v_mfma_i32_16x16x64_i8 v[106:109], v[34:37], v[204:207], v[106:109]
	v_mfma_i32_16x16x64_i8 v[106:109], v[38:41], v[208:211], v[106:109]
	v_mfma_i32_16x16x64_i8 v[138:141], v[58:61], v[174:177], v[138:141]
	v_mfma_i32_16x16x64_i8 v[138:141], v[62:65], v[178:181], v[138:141]
	v_mfma_i32_16x16x64_i8 v[130:133], v[58:61], v[182:185], v[130:133]
	v_mfma_i32_16x16x64_i8 v[130:133], v[62:65], v[186:189], v[130:133]
	v_mfma_i32_16x16x64_i8 v[114:117], v[58:61], v[190:193], v[114:117]
	v_mfma_i32_16x16x64_i8 v[114:117], v[62:65], v[200:203], v[114:117]
	v_mfma_i32_16x16x64_i8 v[98:101], v[58:61], v[204:207], v[98:101]
	v_mfma_i32_16x16x64_i8 v[98:101], v[62:65], v[208:211], v[98:101]
	v_mfma_i32_16x16x64_i8 v[126:129], v[146:149], v[174:177], v[126:129]
	v_mfma_i32_16x16x64_i8 v[126:129], v[150:153], v[178:181], v[126:129]
	v_mfma_i32_16x16x64_i8 v[110:113], v[146:149], v[182:185], v[110:113]
	v_mfma_i32_16x16x64_i8 v[110:113], v[150:153], v[186:189], v[110:113]
	v_mfma_i32_16x16x64_i8 v[94:97], v[146:149], v[190:193], v[94:97]
	v_mfma_i32_16x16x64_i8 v[94:97], v[150:153], v[200:203], v[94:97]
	v_mfma_i32_16x16x64_i8 v[86:89], v[146:149], v[204:207], v[86:89]
	v_mfma_i32_16x16x64_i8 v[86:89], v[150:153], v[208:211], v[86:89]
	v_mfma_i32_16x16x64_i8 v[118:121], v[154:157], v[174:177], v[118:121]
	v_mfma_i32_16x16x64_i8 v[118:121], v[158:161], v[178:181], v[118:121]
	v_mfma_i32_16x16x64_i8 v[102:105], v[154:157], v[182:185], v[102:105]
	v_mfma_i32_16x16x64_i8 v[102:105], v[158:161], v[186:189], v[102:105]
	v_mfma_i32_16x16x64_i8 v[90:93], v[154:157], v[190:193], v[90:93]
	v_mfma_i32_16x16x64_i8 v[90:93], v[158:161], v[200:203], v[90:93]
	v_mfma_i32_16x16x64_i8 v[82:85], v[154:157], v[204:207], v[82:85]
	v_mfma_i32_16x16x64_i8 v[82:85], v[158:161], v[208:211], v[82:85]
	s_barrier
	s_add_i32 s30, s42, s81
	s_add_u32 s98, s28, 0x80
	s_addc_u32 s99, s29, 0
	s_mov_b32 m0, s30
	ds_read_b128 v[174:177], v250 offset:49152
	ds_read_b128 v[178:181], v250 offset:50176
	ds_read_b128 v[182:185], v250 offset:51200
	ds_read_b128 v[186:189], v250 offset:52224
	ds_read_b128 v[190:193], v250 offset:53248
	ds_read_b128 v[200:203], v250 offset:54272
	ds_read_b128 v[204:207], v250 offset:55296
	ds_read_b128 v[208:211], v250 offset:56320
	global_load_lds_dwordx4 v164, s[98:99]
	s_add_i32 m0, s30, 0x2000
	s_add_u32 s28, s28, 0x80080
	s_addc_u32 s29, s29, 0
	s_add_i32 s30, s43, s81
	global_load_lds_dwordx4 v168, s[98:99]
	s_mov_b32 m0, s30
	s_nop 0
	global_load_lds_dwordx4 v164, s[28:29]
	s_add_i32 m0, s30, 0x2000
	s_nop 0
	global_load_lds_dwordx4 v168, s[28:29]
	s_waitcnt vmcnt(6)
	s_waitcnt lgkmcnt(0)
	s_barrier
	s_waitcnt lgkmcnt(0)
	v_mfma_i32_16x16x64_i8 v[78:81], v[34:37], v[174:177], v[78:81]
	v_mfma_i32_16x16x64_i8 v[78:81], v[38:41], v[178:181], v[78:81]
	v_mfma_i32_16x16x64_i8 v[70:73], v[34:37], v[182:185], v[70:73]
	v_mfma_i32_16x16x64_i8 v[70:73], v[38:41], v[186:189], v[70:73]
	v_mfma_i32_16x16x64_i8 v[54:57], v[34:37], v[190:193], v[54:57]
	v_mfma_i32_16x16x64_i8 v[54:57], v[38:41], v[200:203], v[54:57]
	v_mfma_i32_16x16x64_i8 v[2:5], v[34:37], v[204:207], v[2:5]
	v_mfma_i32_16x16x64_i8 v[38:41], v[38:41], v[208:211], v[2:5]
	v_mfma_i32_16x16x64_i8 v[74:77], v[58:61], v[174:177], v[74:77]
	v_mfma_i32_16x16x64_i8 v[74:77], v[62:65], v[178:181], v[74:77]
	v_mfma_i32_16x16x64_i8 v[66:69], v[58:61], v[182:185], v[66:69]
	v_mfma_i32_16x16x64_i8 v[66:69], v[62:65], v[186:189], v[66:69]
	v_mfma_i32_16x16x64_i8 v[50:53], v[58:61], v[190:193], v[50:53]
	v_mfma_i32_16x16x64_i8 v[50:53], v[62:65], v[200:203], v[50:53]
	v_mfma_i32_16x16x64_i8 v[2:5], v[58:61], v[204:207], v[6:9]
	v_mfma_i32_16x16x64_i8 v[34:37], v[62:65], v[208:211], v[2:5]
	v_mfma_i32_16x16x64_i8 v[2:5], v[146:149], v[174:177], v[10:13]
	v_mfma_i32_16x16x64_i8 v[62:65], v[150:153], v[178:181], v[2:5]
	v_mfma_i32_16x16x64_i8 v[2:5], v[154:157], v[174:177], v[14:17]
	v_mfma_i32_16x16x64_i8 v[58:61], v[158:161], v[178:181], v[2:5]
	v_mfma_i32_16x16x64_i8 v[2:5], v[146:149], v[182:185], v[46:49]
	v_mfma_i32_16x16x64_i8 v[46:49], v[150:153], v[186:189], v[2:5]
	v_mfma_i32_16x16x64_i8 v[2:5], v[154:157], v[182:185], v[42:45]
	v_mfma_i32_16x16x64_i8 v[42:45], v[158:161], v[186:189], v[2:5]
	v_mfma_i32_16x16x64_i8 v[2:5], v[146:149], v[190:193], v[30:33]
	v_mfma_i32_16x16x64_i8 v[30:33], v[150:153], v[200:203], v[2:5]
	v_mfma_i32_16x16x64_i8 v[2:5], v[154:157], v[190:193], v[26:29]
	v_mfma_i32_16x16x64_i8 v[26:29], v[158:161], v[200:203], v[2:5]
	v_mfma_i32_16x16x64_i8 v[2:5], v[146:149], v[204:207], v[22:25]
	v_mfma_i32_16x16x64_i8 v[22:25], v[150:153], v[208:211], v[2:5]
	v_mfma_i32_16x16x64_i8 v[2:5], v[154:157], v[204:207], v[18:21]
	v_mfma_i32_16x16x64_i8 v[18:21], v[158:161], v[208:211], v[2:5]
	s_barrier
	s_add_i32 s41, s41, 2
	s_add_u32 s0, s0, 0x100
	s_addc_u32 s1, s1, 0
	s_add_u32 s35, s35, 0x100
	s_addc_u32 s40, s40, 0
	s_cmp_gt_u32 s41, 29
	s_cbranch_scc0 .LBB0_300
	s_and_b64 vcc, exec, s[52:53]
	s_cbranch_vccz .LBB0_303
	s_barrier
